# bias1 loop: next weight-row loads issued before the current row's cross-lane reduction
# baseline (speedup 1.0000x reference)
; __device__ __forceinline__ void bias1_phase(const bf16* W1t, const float* mod1, float* biasp, int G) {
;     int tid = threadIdx.x; asm volatile("" : "+v"(tid)); const int lane = tid & 63, wave = tid >> 6;
;     for (int p = blockIdx.x * NWAVES + wave; p < 4112; p += G * NWAVES) {
;         float s0 = 0.f, s1 = 0.f;
; #pragma unroll
;         for (int j = 0; j < 2; ++j) { const int k0 = 8 * lane + 512 * j; const v4u w = *(const v4u*)(W1t + (size_t)p * D + k0);
; #pragma unroll
.LBB0_470:
	v_mov_b32_e32 v1, v216
	v_readlane_b32 s0, v249, 3
	v_ashrrev_i32_e32 v0, 6, v1
	s_nop 0
	v_add_u32_e32 v0, s0, v0
	s_movk_i32 s0, 0x1010
	v_cmp_gt_i32_e32 vcc, s0, v0
	s_and_saveexec_b64 s[0:1], vcc
	v_readlane_b32 s24, v249, 5
	v_readlane_b32 s25, v249, 6
	s_cbranch_execz .LBB0_475
	v_cmp_lt_i32_e32 vcc, v215, v209
	v_and_b32_e32 v20, 63, v1
	s_add_u32 s14, s10, 0x26000
	v_cndmask_b32_e32 v1, v208, v215, vcc
	v_cmp_lt_i32_e32 vcc, v214, v209
	v_lshlrev_b32_e32 v14, 2, v1
	s_addc_u32 s15, s11, 0
	v_cndmask_b32_e32 v1, v208, v214, vcc
	v_cmp_lt_i32_e32 vcc, v213, v209
	v_lshlrev_b32_e32 v15, 2, v1
	v_lshlrev_b32_e32 v6, 5, v20
	v_cndmask_b32_e32 v1, v208, v213, vcc
	v_cmp_lt_i32_e32 vcc, v212, v209
	v_lshlrev_b32_e32 v16, 2, v1
	v_mov_b32_e32 v7, 0
	v_cndmask_b32_e32 v1, v208, v212, vcc
	v_cmp_lt_i32_e32 vcc, v211, v209
	v_lshlrev_b32_e32 v17, 2, v1
	v_lshl_add_u64 v[2:3], s[14:15], 0, v[6:7]
	v_cndmask_b32_e32 v1, v208, v211, vcc
	v_cmp_lt_i32_e32 vcc, v210, v209
	v_lshlrev_b32_e32 v18, 2, v1
	v_or_b32_e32 v6, 0x800, v6
	v_cndmask_b32_e32 v1, v208, v210, vcc
	v_lshlrev_b32_e32 v19, 2, v1
	v_ashrrev_i32_e32 v1, 31, v0
	v_lshlrev_b64 v[12:13], 11, v[0:1]
	v_lshl_add_u64 v[6:7], s[14:15], 0, v[6:7]
	v_lshl_add_u64 v[10:11], v[0:1], 2, s[10:11]
	s_mov_b64 s[14:15], 0x140000
	v_lshl_or_b32 v12, v20, 4, v12
	s_mov_b64 s[16:17], 0x3000
	v_lshl_add_u64 v[10:11], v[10:11], 0, s[14:15]
	s_ashr_i32 s5, s4, 31
	v_lshl_add_u64 v[12:13], s[10:11], 0, v[12:13]
	s_mov_b64 s[14:15], 0xa00000
	v_cmp_eq_u32_e64 s[38:39], 0, v20
	v_lshl_add_u64 v[4:5], v[2:3], 0, s[16:17]
	v_lshl_add_u64 v[8:9], v[6:7], 0, s[16:17]
	s_lshl_b64 s[40:41], s[4:5], 2
	v_lshl_add_u64 v[12:13], v[12:13], 0, s[14:15]
	s_lshl_b64 s[42:43], s[4:5], 11
	s_mov_b64 s[44:45], 0
	s_mov_b32 s32, 0
	s_branch .LBB0_473

; __device__ __forceinline__ float bflo(unsigned w) { return __uint_as_float(w << 16); }
; __device__ __forceinline__ float bfhi(unsigned w) { return __uint_as_float(w & 0xffff0000u); }
; __device__ __forceinline__ void bias1_phase(const bf16* W1t, const float* mod1, float* biasp, int G) {
;     ...
;     for (int p = blockIdx.x * NWAVES + wave; p < 4112; p += G * NWAVES) {
;         float s0 = 0.f, s1 = 0.f;
; #pragma unroll
;         for (int j = 0; j < 2; ++j) { const int k0 = 8 * lane + 512 * j; const v4u w = *(const v4u*)(W1t + (size_t)p * D + k0);
; #pragma unroll
;             for (int e = 0; e < 4; ++e) { const float wl = bflo(w[e]), wh = bfhi(w[e]);
;                 s0 += wl * mod1[k0 + 2 * e] + wh * mod1[k0 + 2 * e + 1]; s1 += wl * mod1[3072 + k0 + 2 * e] + wh * mod1[3072 + k0 + 2 * e + 1]; } }
;         s0 = wave_sum(s0); s1 = wave_sum(s1);
;         if (lane == 0) { biasp[p] = s0; biasp[4352 + p] = s1; }
;     }
.LBB0_473:
	s_waitcnt lgkmcnt(0)
	s_cmp_eq_u32 s32, 1
	s_cbranch_scc1 .Lb1_skipld
	global_load_dwordx4 v[20:23], v[12:13], off
	global_load_dwordx4 v[24:27], v[12:13], off offset:1024
.Lb1_skipld:
	global_load_dwordx4 v[28:31], v[2:3], off
	global_load_dwordx4 v[32:35], v[4:5], off
	global_load_dwordx4 v[36:39], v[2:3], off offset:16
	global_load_dwordx4 v[40:43], v[4:5], off offset:16
	global_load_dwordx4 v[44:47], v[6:7], off
	global_load_dwordx4 v[48:51], v[8:9], off
	global_load_dwordx4 v[52:55], v[6:7], off offset:16
	global_load_dwordx4 v[56:59], v[8:9], off offset:16
	s_cmp_eq_u32 s32, 1
	s_cbranch_scc0 .Lb1_w9
	s_waitcnt vmcnt(8)
	v_mov_b64_e32 v[20:21], v[70:71]
	v_mov_b64_e32 v[22:23], v[72:73]
	v_mov_b64_e32 v[24:25], v[74:75]
	v_mov_b64_e32 v[26:27], v[76:77]
.Lb1_w9:
	s_waitcnt vmcnt(9)
	v_lshlrev_b32_e32 v1, 16, v20
	v_and_b32_e32 v20, 0xffff0000, v20
	v_lshlrev_b32_e32 v60, 16, v21
	v_and_b32_e32 v21, 0xffff0000, v21
	s_waitcnt vmcnt(7)
	v_mul_f32_e32 v29, v29, v20
	s_waitcnt vmcnt(6)
	v_mul_f32_e32 v20, v33, v20
	v_lshlrev_b32_e32 v61, 16, v22
	v_and_b32_e32 v22, 0xffff0000, v22
	v_mul_f32_e32 v31, v31, v21
	v_mul_f32_e32 v21, v35, v21
	v_fmac_f32_e32 v29, v28, v1
	v_fmac_f32_e32 v20, v32, v1
	v_lshlrev_b32_e32 v62, 16, v23
	v_and_b32_e32 v23, 0xffff0000, v23
	s_waitcnt vmcnt(5)
	v_mul_f32_e32 v33, v37, v22
	s_waitcnt vmcnt(4)
	v_mul_f32_e32 v22, v41, v22
	v_fmac_f32_e32 v31, v30, v60
	v_fmac_f32_e32 v21, v34, v60
	v_add_f32_e32 v1, 0, v29
	v_add_f32_e32 v20, 0, v20
	v_lshlrev_b32_e32 v63, 16, v24
	v_and_b32_e32 v24, 0xffff0000, v24
	v_mul_f32_e32 v35, v39, v23
	v_mul_f32_e32 v23, v43, v23
	v_fmac_f32_e32 v33, v36, v61
	v_fmac_f32_e32 v22, v40, v61
	v_add_f32_e32 v1, v1, v31
	v_add_f32_e32 v20, v20, v21
	v_lshlrev_b32_e32 v64, 16, v25
	v_and_b32_e32 v25, 0xffff0000, v25
	s_waitcnt vmcnt(3)
	v_mul_f32_e32 v37, v45, v24
	s_waitcnt vmcnt(2)
	v_mul_f32_e32 v24, v49, v24
	v_fmac_f32_e32 v35, v38, v62
	v_fmac_f32_e32 v23, v42, v62
	v_add_f32_e32 v1, v1, v33
	v_add_f32_e32 v20, v20, v22
	v_lshlrev_b32_e32 v65, 16, v26
	v_and_b32_e32 v26, 0xffff0000, v26
	v_mul_f32_e32 v39, v47, v25
	v_mul_f32_e32 v25, v51, v25
	v_fmac_f32_e32 v37, v44, v63
	v_fmac_f32_e32 v24, v48, v63
	v_add_f32_e32 v1, v1, v35
	v_add_f32_e32 v20, v20, v23
	v_lshlrev_b32_e32 v66, 16, v27
	v_and_b32_e32 v27, 0xffff0000, v27
	s_waitcnt vmcnt(1)
	v_mul_f32_e32 v41, v53, v26
	s_waitcnt vmcnt(0)
	v_mul_f32_e32 v26, v57, v26
	v_fmac_f32_e32 v39, v46, v64
	v_fmac_f32_e32 v25, v50, v64
	v_add_f32_e32 v1, v1, v37
	v_add_f32_e32 v20, v20, v24
	v_mul_f32_e32 v43, v55, v27
	v_mul_f32_e32 v27, v59, v27
	v_fmac_f32_e32 v41, v52, v65
	v_fmac_f32_e32 v26, v56, v65
	v_add_f32_e32 v1, v1, v39
	v_add_f32_e32 v20, v20, v25
	v_fmac_f32_e32 v43, v54, v66
	v_fmac_f32_e32 v27, v58, v66
	v_add_f32_e32 v1, v1, v41
	v_add_f32_e32 v20, v20, v26
	v_add_f32_e32 v1, v1, v43
	v_add_f32_e32 v20, v20, v27
	v_lshl_add_u64 v[78:79], v[12:13], 0, s[42:43]
	global_load_dwordx4 v[70:73], v[78:79], off
	global_load_dwordx4 v[74:77], v[78:79], off offset:1024
	s_mov_b32 s32, 1
	ds_bpermute_b32 v21, v14, v1
	ds_bpermute_b32 v22, v14, v20
	s_waitcnt lgkmcnt(1)
	v_add_f32_e32 v1, v1, v21
	s_waitcnt lgkmcnt(0)
	v_add_f32_e32 v20, v20, v22
	ds_bpermute_b32 v21, v15, v1
	ds_bpermute_b32 v22, v15, v20
	s_waitcnt lgkmcnt(1)
	v_add_f32_e32 v1, v1, v21
	s_waitcnt lgkmcnt(0)
	v_add_f32_e32 v20, v20, v22
	ds_bpermute_b32 v21, v16, v1
	ds_bpermute_b32 v22, v16, v20
	s_waitcnt lgkmcnt(1)
	v_add_f32_e32 v1, v1, v21
	s_waitcnt lgkmcnt(0)
	v_add_f32_e32 v20, v20, v22
	ds_bpermute_b32 v21, v17, v1
	ds_bpermute_b32 v22, v17, v20
	s_waitcnt lgkmcnt(1)
	v_add_f32_e32 v1, v1, v21
	s_waitcnt lgkmcnt(0)
	v_add_f32_e32 v20, v20, v22
	ds_bpermute_b32 v21, v18, v1
	ds_bpermute_b32 v22, v18, v20
	s_waitcnt lgkmcnt(1)
	v_add_f32_e32 v1, v1, v21
	s_waitcnt lgkmcnt(0)
	v_add_f32_e32 v20, v20, v22
	ds_bpermute_b32 v21, v19, v1
	ds_bpermute_b32 v22, v19, v20
	s_and_saveexec_b64 s[18:19], s[38:39]
	s_cbranch_execz .LBB0_472
	s_waitcnt lgkmcnt(0)
	v_add_f32_e32 v22, v20, v22
	v_add_co_u32_e32 v20, vcc, 0x4000, v10
	v_add_f32_e32 v1, v1, v21
	s_nop 0
	v_addc_co_u32_e32 v21, vcc, 0, v11, vcc
	global_store_dword v[10:11], v1, off
	global_store_dword v[20:21], v22, off offset:1024
	s_branch .LBB0_472
